# v48 + z-tile loads issued inside conv group 3, LDS write right after barrier 1
# baseline (speedup 1.0000x reference)
.LBB0_364:
	s_or_b64 exec, exec, s[94:95]
	s_waitcnt vmcnt(8)
	v_add_u32_e32 v190, s13, v231
	v_ashrrev_i32_e32 v191, 31, v190
	v_lshlrev_b64 v[190:191], 12, v[190:191]
	v_lshl_add_u64 v[190:191], v[164:165], 0, v[190:191]
	global_load_dwordx4 v[136:139], v[190:191], off
	v_lshlrev_b32_e32 v84, 16, v106
	v_and_b32_e32 v85, 0xffff0000, v106
	v_pk_fma_f32 v[72:73], v[172:173], v[84:85], v[174:175]
	v_lshlrev_b32_e32 v92, 16, v102
	v_pk_fma_f32 v[72:73], v[170:171], v[78:79], v[72:73]
	v_and_b32_e32 v93, 0xffff0000, v102
	v_pk_fma_f32 v[72:73], v[168:169], v[80:81], v[72:73]
	s_nop 0
	v_pk_fma_f32 v[72:73], v[166:167], v[82:83], v[72:73]
	v_lshlrev_b32_e32 v82, 16, v105
	v_pk_mul_f32 v[74:75], v[72:73], s[96:97] op_sel_hi:[1,0]
	v_and_b32_e32 v83, 0xffff0000, v105
	v_exp_f32_e32 v74, v74
	v_exp_f32_e32 v75, v75
	s_nop 0
	v_pk_add_f32 v[74:75], v[74:75], 1.0 op_sel_hi:[1,0]
	s_nop 0
	v_rcp_f32_e32 v74, v74
	v_rcp_f32_e32 v75, v75
	s_nop 0
	v_pk_mul_f32 v[72:73], v[72:73], v[74:75]
	v_pk_fma_f32 v[74:75], v[172:173], v[82:83], v[174:175]
	s_nop 0
	v_pk_fma_f32 v[74:75], v[170:171], v[84:85], v[74:75]
	s_nop 0
	v_pk_fma_f32 v[74:75], v[168:169], v[78:79], v[74:75]
	s_nop 0
	v_pk_fma_f32 v[74:75], v[166:167], v[80:81], v[74:75]
	v_lshlrev_b32_e32 v80, 16, v104
	v_pk_mul_f32 v[76:77], v[74:75], s[96:97] op_sel_hi:[1,0]
	v_and_b32_e32 v81, 0xffff0000, v104
	v_exp_f32_e32 v76, v76
	global_load_dwordx4 v[140:143], v[190:191], off offset:128
	v_exp_f32_e32 v77, v77
	s_nop 0
	v_pk_add_f32 v[76:77], v[76:77], 1.0 op_sel_hi:[1,0]
	s_nop 0
	v_rcp_f32_e32 v76, v76
	v_rcp_f32_e32 v77, v77
	s_nop 0
	v_pk_mul_f32 v[74:75], v[74:75], v[76:77]
	v_pk_fma_f32 v[76:77], v[172:173], v[80:81], v[174:175]
	s_nop 0
	v_pk_fma_f32 v[76:77], v[170:171], v[82:83], v[76:77]
	s_nop 0
	v_pk_fma_f32 v[76:77], v[168:169], v[84:85], v[76:77]
	s_nop 0
	v_pk_fma_f32 v[76:77], v[166:167], v[78:79], v[76:77]
	s_nop 0
	v_pk_mul_f32 v[78:79], v[76:77], s[96:97] op_sel_hi:[1,0]
	s_nop 0
	v_exp_f32_e32 v78, v78
	v_exp_f32_e32 v79, v79
	s_nop 0
	v_pk_add_f32 v[78:79], v[78:79], 1.0 op_sel_hi:[1,0]
	s_nop 0
	v_rcp_f32_e32 v78, v78
	v_rcp_f32_e32 v79, v79
	s_nop 0
	v_pk_mul_f32 v[76:77], v[76:77], v[78:79]
	v_lshlrev_b32_e32 v78, 16, v103
	v_and_b32_e32 v79, 0xffff0000, v103
	v_pk_fma_f32 v[86:87], v[172:173], v[78:79], v[174:175]
	s_nop 0
	v_pk_fma_f32 v[86:87], v[170:171], v[80:81], v[86:87]
	global_load_dwordx4 v[144:147], v[190:191], off offset:256
	s_nop 0
	v_pk_fma_f32 v[86:87], v[168:169], v[82:83], v[86:87]
	s_nop 0
	v_pk_fma_f32 v[84:85], v[166:167], v[84:85], v[86:87]
	s_nop 0
	v_pk_mul_f32 v[86:87], v[84:85], s[96:97] op_sel_hi:[1,0]
	s_nop 0
	v_exp_f32_e32 v86, v86
	v_exp_f32_e32 v87, v87
	s_nop 0
	v_pk_add_f32 v[86:87], v[86:87], 1.0 op_sel_hi:[1,0]
	s_nop 0
	v_rcp_f32_e32 v86, v86
	v_rcp_f32_e32 v87, v87
	s_nop 0
	v_pk_mul_f32 v[84:85], v[84:85], v[86:87]
	v_pk_fma_f32 v[86:87], v[172:173], v[92:93], v[174:175]
	s_nop 0
	v_pk_fma_f32 v[86:87], v[170:171], v[78:79], v[86:87]
	s_nop 0
	v_pk_fma_f32 v[86:87], v[168:169], v[80:81], v[86:87]
	s_nop 0
	v_pk_fma_f32 v[82:83], v[166:167], v[82:83], v[86:87]
	s_nop 0
	v_pk_mul_f32 v[86:87], v[82:83], s[96:97] op_sel_hi:[1,0]
	s_nop 0
	v_exp_f32_e32 v86, v86
	v_exp_f32_e32 v87, v87
	s_nop 0
	v_pk_add_f32 v[86:87], v[86:87], 1.0 op_sel_hi:[1,0]
	s_nop 0
	v_rcp_f32_e32 v86, v86
	global_load_dwordx4 v[148:151], v[190:191], off offset:384
	v_rcp_f32_e32 v87, v87
	s_nop 0
	v_pk_mul_f32 v[86:87], v[82:83], v[86:87]
	v_lshlrev_b32_e32 v82, 16, v101
	v_and_b32_e32 v83, 0xffff0000, v101
	v_pk_fma_f32 v[88:89], v[172:173], v[82:83], v[174:175]
	s_nop 0
	v_pk_fma_f32 v[88:89], v[170:171], v[92:93], v[88:89]
	s_nop 0
	v_pk_fma_f32 v[88:89], v[168:169], v[78:79], v[88:89]
	s_nop 0
	v_pk_fma_f32 v[80:81], v[166:167], v[80:81], v[88:89]
	s_nop 0
	v_pk_mul_f32 v[88:89], v[80:81], s[96:97] op_sel_hi:[1,0]
	s_nop 0
	v_exp_f32_e32 v88, v88
	v_exp_f32_e32 v89, v89
	s_nop 0
	v_pk_add_f32 v[88:89], v[88:89], 1.0 op_sel_hi:[1,0]
	s_nop 0
	v_rcp_f32_e32 v88, v88
	v_rcp_f32_e32 v89, v89
	s_nop 0
	v_pk_mul_f32 v[88:89], v[80:81], v[88:89]
	v_lshlrev_b32_e32 v80, 16, v100
	v_and_b32_e32 v81, 0xffff0000, v100
	v_pk_fma_f32 v[90:91], v[172:173], v[80:81], v[174:175]
	s_nop 0
	v_pk_fma_f32 v[90:91], v[170:171], v[82:83], v[90:91]
	s_nop 0
	v_pk_fma_f32 v[90:91], v[168:169], v[92:93], v[90:91]
	s_nop 0
	v_pk_fma_f32 v[78:79], v[166:167], v[78:79], v[90:91]
	s_nop 0
	v_pk_mul_f32 v[90:91], v[78:79], s[96:97] op_sel_hi:[1,0]
	s_nop 0
	v_exp_f32_e32 v90, v90
	v_exp_f32_e32 v91, v91
	s_nop 0
	v_pk_add_f32 v[90:91], v[90:91], 1.0 op_sel_hi:[1,0]
	s_nop 0
	v_rcp_f32_e32 v90, v90
	v_rcp_f32_e32 v91, v91
	s_nop 0
	v_pk_mul_f32 v[90:91], v[78:79], v[90:91]
	v_lshlrev_b32_e32 v78, 16, v99
	v_and_b32_e32 v79, 0xffff0000, v99
	v_pk_fma_f32 v[100:101], v[172:173], v[78:79], v[174:175]
	s_nop 0
	v_pk_fma_f32 v[100:101], v[170:171], v[80:81], v[100:101]
	s_nop 0
	v_pk_fma_f32 v[100:101], v[168:169], v[82:83], v[100:101]
	s_nop 0
	v_pk_fma_f32 v[92:93], v[166:167], v[92:93], v[100:101]
	s_nop 0
	v_pk_mul_f32 v[100:101], v[92:93], s[96:97] op_sel_hi:[1,0]
	s_nop 0
	v_exp_f32_e32 v100, v100
	v_exp_f32_e32 v101, v101
	s_nop 0
	v_pk_add_f32 v[100:101], v[100:101], 1.0 op_sel_hi:[1,0]
	s_nop 0
	v_rcp_f32_e32 v100, v100
	v_rcp_f32_e32 v101, v101
	s_nop 0
	v_pk_mul_f32 v[92:93], v[92:93], v[100:101]
	s_and_saveexec_b64 s[16:17], s[4:5]
	s_xor_b64 s[94:95], exec, s[16:17]
	s_cbranch_execz .LBB0_370
	s_and_saveexec_b64 s[16:17], s[8:9]
	s_xor_b64 vcc, exec, s[16:17]
	s_cbranch_execz .LBB0_367
	v_cvt_pk_bf16_f32 v72, v72, v73
	v_add_u32_e32 v73, v205, v219
	ds_write_b32 v73, v72 offset:1408
	v_cvt_pk_bf16_f32 v72, v74, v75
	ds_write_b32 v212, v72 offset:3856
	v_cvt_pk_bf16_f32 v72, v76, v77
	ds_write_b32 v212, v72 offset:4128
	v_cvt_pk_bf16_f32 v72, v84, v85
	ds_write_b32 v212, v72 offset:4400
	v_cvt_pk_bf16_f32 v72, v86, v87
	ds_write_b32 v212, v72 offset:4672
	v_cvt_pk_bf16_f32 v72, v88, v89
	ds_write_b32 v212, v72 offset:4944
	v_cvt_pk_bf16_f32 v72, v90, v91
	ds_write_b32 v212, v72 offset:5216
	v_cvt_pk_bf16_f32 v72, v92, v93
	ds_write_b32 v212, v72 offset:5488

.LBB0_372:
	s_or_b64 exec, exec, s[94:95]
	s_cmp_eq_u32 s15, s1
	s_cselect_b64 s[16:17], -1, 0
	s_and_b64 s[16:17], s[6:7], s[16:17]
	s_waitcnt vmcnt(6)
	v_lshlrev_b32_e32 v2, 16, v3
	v_and_b32_e32 v3, 0xffff0000, v3
	s_waitcnt vmcnt(5)
	v_lshlrev_b32_e32 v68, 16, v69
	v_and_b32_e32 v69, 0xffff0000, v69
	s_waitcnt vmcnt(4)
	v_lshlrev_b32_e32 v70, 16, v71
	v_and_b32_e32 v71, 0xffff0000, v71
	s_and_saveexec_b64 s[94:95], s[16:17]
	s_cbranch_execz .LBB0_348
	global_store_dwordx2 v[160:161], v[2:3], off
	global_store_dwordx2 v[182:183], v[68:69], off
	global_store_dwordx2 v[184:185], v[70:71], off

.LBB0_380:
	s_or_b64 exec, exec, s[94:95]
	s_add_i32 s14, s15, 1
	s_cmp_lt_u32 s14, s0
	s_cselect_b32 s15, s14, s15
	s_lshl_b32 s16, s15, 6
	s_add_i32 s16, s16, s97
	s_cmp_eq_u32 s15, 0
	s_cselect_b32 s15, 0, 0x1000
	s_waitcnt lgkmcnt(0)
	s_barrier
	s_waitcnt vmcnt(0)
	ds_write_b128 v230, v[136:139]
	ds_write_b128 v230, v[140:143] offset:128
	ds_write_b128 v230, v[144:147] offset:256
	ds_write_b128 v230, v[148:151] offset:384
	v_readlane_b32 s98, v254, 52
	v_readlane_b32 s99, v254, 53
	v_readfirstlane_b32 s100, v1
	s_nop 3
	v_subrev_u32_e32 v151, s98, v176
	s_cmp_lg_u32 s100, 0
	s_cselect_b32 s101, 0x1000, s15
	s_add_i32 s100, s100, s16
	s_lshl_b32 s100, s100, 13
	s_add_u32 s98, s98, s100
	s_addc_u32 s99, s99, 0
	s_mul_i32 s100, s101, 6
	s_sub_u32 s98, s98, s100
	s_subb_u32 s99, s99, 0
	s_lshl_b32 s100, s101, 1
	v_add_u32_e32 v2, s16, v159
	v_ashrrev_i32_e32 v3, 31, v2
	v_lshlrev_b64 v[2:3], 7, v[2:3]
	v_lshl_add_u64 v[2:3], s[90:91], 0, v[2:3]
	global_load_dword v153, v[2:3], off
	ds_read_b128 v[84:87], v180
	ds_read_b128 v[88:91], v181 offset:17408
	ds_read_b128 v[92:95], v181 offset:21760
	global_load_dword v250, v151, s[98:99]
	ds_read_b128 v[68:71], v180 offset:64
	ds_read_b128 v[96:99], v181 offset:17472
	ds_read_b128 v[100:103], v181 offset:21824
	ds_read_b128 v[72:75], v180 offset:128
	ds_read_b128 v[76:79], v181 offset:17536
	v_add_u32_e32 v192, v178, v228
	ds_read_b128 v[80:83], v181 offset:21888
	ds_read_b128 v[104:107], v180 offset:192
	s_waitcnt lgkmcnt(8)
	v_mfma_f32_16x16x32_bf16 v[88:91], v[84:87], v[88:91], 0
	s_add_u32 s98, s98, s100
	s_addc_u32 s99, s99, 0
	global_load_dword v251, v151, s[98:99]
	ds_read_b128 v[108:111], v181 offset:17600
	s_waitcnt lgkmcnt(8)
	v_mfma_f32_16x16x32_bf16 v[84:87], v[84:87], v[92:95], 0
	ds_read_b128 v[112:115], v181 offset:21952
	s_waitcnt lgkmcnt(7)
	v_mfma_f32_16x16x32_bf16 v[88:91], v[68:71], v[96:99], v[88:91]
	s_waitcnt lgkmcnt(6)
	v_mfma_f32_16x16x32_bf16 v[84:87], v[68:71], v[100:103], v[84:87]
	s_waitcnt lgkmcnt(4)
	v_mfma_f32_16x16x32_bf16 v[88:91], v[72:75], v[76:79], v[88:91]
	s_add_u32 s98, s98, s100
	s_addc_u32 s99, s99, 0
	global_load_dword v252, v151, s[98:99]
	s_waitcnt lgkmcnt(3)
	v_mfma_f32_16x16x32_bf16 v[84:87], v[72:75], v[80:83], v[84:87]
	s_waitcnt lgkmcnt(1)
	v_mfma_f32_16x16x32_bf16 v[88:91], v[104:107], v[108:111], v[88:91]
	s_waitcnt lgkmcnt(0)
	v_mfma_f32_16x16x32_bf16 v[84:87], v[104:107], v[112:115], v[84:87]
	s_nop 7
	ds_write2_b32 v202, v88, v84 offset1:16
	ds_write2_b32 v202, v89, v85 offset0:68 offset1:84
	ds_write2_b32 v202, v90, v86 offset0:136 offset1:152
	s_add_u32 s98, s98, s100
	s_addc_u32 s99, s99, 0
	global_load_dword v249, v151, s[98:99]
	ds_write2_b32 v202, v91, v87 offset0:204 offset1:220
	ds_read2_b64 v[92:95], v224 offset1:4
	ds_read2_b64 v[100:103], v225 offset1:4
	ds_read2_b64 v[108:111], v226 offset1:4
	ds_read2_b64 v[116:119], v227 offset1:4
	ds_read2_b64 v[124:127], v224 offset0:8 offset1:12
	ds_read2_b64 v[68:71], v225 offset0:8 offset1:12
	ds_read2_b64 v[72:75], v226 offset0:8 offset1:12
	ds_read2_b64 v[76:79], v227 offset0:8 offset1:12
	v_cvt_pk_bf16_f32 v84, v4, v5
	s_add_u32 s98, s98, 0x2000
	s_addc_u32 s99, s99, 0
	global_load_dword v248, v151, s[98:99]
	v_cvt_pk_bf16_f32 v85, v6, v7
	v_cvt_pk_bf16_f32 v86, v12, v13
	v_cvt_pk_bf16_f32 v87, v14, v15
	v_cvt_pk_bf16_f32 v88, v8, v9
	v_cvt_pk_bf16_f32 v89, v10, v11
	v_cvt_pk_bf16_f32 v90, v16, v17
	v_cvt_pk_bf16_f32 v91, v18, v19
	ds_read2_b64 v[80:83], v224 offset0:16 offset1:20
	s_waitcnt lgkmcnt(8)
	v_mfma_f32_16x16x32_bf16 v[96:99], v[92:95], v[84:87], 0
	s_add_u32 s98, s98, 0x2000
	s_addc_u32 s99, s99, 0
	global_load_dword v247, v151, s[98:99]
	v_mfma_f32_16x16x32_bf16 v[92:95], v[92:95], v[88:91], 0
	ds_read2_b64 v[128:131], v225 offset0:16 offset1:20
	s_waitcnt lgkmcnt(8)
	v_mfma_f32_16x16x32_bf16 v[104:107], v[100:103], v[84:87], 0
	v_mfma_f32_16x16x32_bf16 v[100:103], v[100:103], v[88:91], 0
	ds_read2_b64 v[132:135], v226 offset0:16 offset1:20
	s_waitcnt lgkmcnt(8)
	v_mfma_f32_16x16x32_bf16 v[112:115], v[108:111], v[84:87], 0
	v_mfma_f32_16x16x32_bf16 v[108:111], v[108:111], v[88:91], 0
	ds_read2_b64 v[136:139], v227 offset0:16 offset1:20
	s_add_u32 s98, s98, 0x2000
	s_addc_u32 s99, s99, 0
	global_load_dword v246, v151, s[98:99]
	s_waitcnt lgkmcnt(8)
	v_mfma_f32_16x16x32_bf16 v[84:87], v[116:119], v[84:87], 0
	v_mfma_f32_16x16x32_bf16 v[88:91], v[116:119], v[88:91], 0
	v_cvt_pk_bf16_f32 v116, v20, v21
	v_cvt_pk_bf16_f32 v117, v22, v23
	v_cvt_pk_bf16_f32 v118, v28, v29
	v_cvt_pk_bf16_f32 v119, v30, v31
	v_cvt_pk_bf16_f32 v120, v24, v25
	v_cvt_pk_bf16_f32 v121, v26, v27
	v_cvt_pk_bf16_f32 v122, v32, v33
	s_add_u32 s98, s98, 0x2000
	s_addc_u32 s99, s99, 0
	global_load_dword v245, v151, s[98:99]
	v_cvt_pk_bf16_f32 v123, v34, v35
	ds_read2_b64 v[140:143], v224 offset0:24 offset1:28
	s_waitcnt lgkmcnt(8)
	v_mfma_f32_16x16x32_bf16 v[96:99], v[124:127], v[116:119], v[96:99]
	v_mfma_f32_16x16x32_bf16 v[92:95], v[124:127], v[120:123], v[92:95]
	ds_read2_b64 v[144:147], v225 offset0:24 offset1:28
	s_waitcnt lgkmcnt(8)
	v_mfma_f32_16x16x32_bf16 v[104:107], v[68:71], v[116:119], v[104:107]
	v_mfma_f32_16x16x32_bf16 v[100:103], v[68:71], v[120:123], v[100:103]
	s_waitcnt lgkmcnt(7)
	s_add_u32 s98, s98, 0x2000
	s_addc_u32 s99, s99, 0
	global_load_dword v244, v151, s[98:99]
	v_mfma_f32_16x16x32_bf16 v[112:115], v[72:75], v[116:119], v[112:115]
	v_mfma_f32_16x16x32_bf16 v[108:111], v[72:75], v[120:123], v[108:111]
	s_waitcnt lgkmcnt(6)
	v_mfma_f32_16x16x32_bf16 v[84:87], v[76:79], v[116:119], v[84:87]
	v_cvt_pk_bf16_f32 v116, v36, v37
	v_cvt_pk_bf16_f32 v117, v38, v39
	v_cvt_pk_bf16_f32 v118, v44, v45
	v_mfma_f32_16x16x32_bf16 v[88:91], v[76:79], v[120:123], v[88:91]
	v_cvt_pk_bf16_f32 v119, v46, v47
	v_cvt_pk_bf16_f32 v120, v40, v41
	s_add_u32 s98, s98, 0x2000
	s_addc_u32 s99, s99, 0
	global_load_dword v243, v151, s[98:99]
	v_cvt_pk_bf16_f32 v121, v42, v43
	v_cvt_pk_bf16_f32 v122, v48, v49
	v_cvt_pk_bf16_f32 v123, v50, v51
	s_waitcnt lgkmcnt(5)
	v_mfma_f32_16x16x32_bf16 v[96:99], v[80:83], v[116:119], v[96:99]
	v_mfma_f32_16x16x32_bf16 v[92:95], v[80:83], v[120:123], v[92:95]
	s_waitcnt lgkmcnt(4)
	v_mfma_f32_16x16x32_bf16 v[104:107], v[128:131], v[116:119], v[104:107]
	v_mfma_f32_16x16x32_bf16 v[100:103], v[128:131], v[120:123], v[100:103]
	s_waitcnt lgkmcnt(3)
	s_add_u32 s98, s98, 0x2000
	s_addc_u32 s99, s99, 0
	global_load_dword v242, v151, s[98:99]
	v_mfma_f32_16x16x32_bf16 v[112:115], v[132:135], v[116:119], v[112:115]
	v_mfma_f32_16x16x32_bf16 v[108:111], v[132:135], v[120:123], v[108:111]
	s_waitcnt lgkmcnt(2)
	v_mfma_f32_16x16x32_bf16 v[84:87], v[136:139], v[116:119], v[84:87]
	v_mfma_f32_16x16x32_bf16 v[116:119], v[136:139], v[120:123], v[88:91]
	s_nop 2
	v_cvt_pk_bf16_f32 v88, v52, v53
	v_cvt_pk_bf16_f32 v89, v54, v55
	v_cvt_pk_bf16_f32 v90, v60, v61
	v_cvt_pk_bf16_f32 v91, v62, v63
	s_add_u32 s98, s98, 0x2000
	s_addc_u32 s99, s99, 0
	global_load_dword v241, v151, s[98:99]
	v_cvt_pk_bf16_f32 v120, v56, v57
	v_cvt_pk_bf16_f32 v121, v58, v59
	v_cvt_pk_bf16_f32 v122, v64, v65
	v_cvt_pk_bf16_f32 v123, v66, v67
	s_waitcnt lgkmcnt(1)
	v_mfma_f32_16x16x32_bf16 v[128:131], v[140:143], v[88:91], v[96:99]
	v_mfma_f32_16x16x32_bf16 v[124:127], v[140:143], v[120:123], v[92:95]
	s_nop 2
	ds_read2_b64 v[92:95], v226 offset0:24 offset1:28
	s_nop 2
	s_add_u32 s98, s98, 0x2000
	s_addc_u32 s99, s99, 0
	global_load_dword v240, v151, s[98:99]
	s_waitcnt lgkmcnt(1)
	v_mfma_f32_16x16x32_bf16 v[104:107], v[144:147], v[88:91], v[104:107]
	v_mfma_f32_16x16x32_bf16 v[132:135], v[144:147], v[120:123], v[100:103]
	s_waitcnt lgkmcnt(0)
	v_mfma_f32_16x16x32_bf16 v[100:103], v[92:95], v[88:91], v[112:115]
	v_mfma_f32_16x16x32_bf16 v[96:99], v[92:95], v[120:123], v[108:111]
	ds_read2_b64 v[92:95], v227 offset0:24 offset1:28
	s_waitcnt lgkmcnt(0)
	v_mfma_f32_16x16x32_bf16 v[88:91], v[92:95], v[88:91], v[84:87]
	v_mfma_f32_16x16x32_bf16 v[92:95], v[92:95], v[120:123], v[116:119]
	s_add_u32 s98, s98, 0x2000
	s_addc_u32 s99, s99, 0
	global_load_dword v239, v151, s[98:99]
	v_add_u32_e32 v120, s33, v156
	s_nop 0
	ds_read_b128 v[84:87], v120
	ds_read_b128 v[68:71], v120 offset:64
	ds_read_b128 v[72:75], v120 offset:128
	s_nop 0
	s_waitcnt lgkmcnt(2)
	v_mul_f32_e32 v2, 0x3fb8aa3b, v84
	v_mul_f32_e32 v84, 0x3fb8aa3b, v86
	v_exp_f32_e32 v108, v84
	s_add_u32 s98, s98, 0x2000
	s_addc_u32 s99, s99, 0
	global_load_dword v238, v151, s[98:99]
	v_mul_f32_e32 v84, 0x3fb8aa3b, v87
	v_exp_f32_e32 v109, v84
	v_mul_f32_e32 v3, 0x3fb8aa3b, v85
	v_exp_f32_e32 v2, v2
	v_exp_f32_e32 v3, v3
	v_pk_mul_f32 v[86:87], v[130:131], v[108:109]
	v_pk_mul_f32 v[118:119], v[126:127], v[108:109]
	v_pk_mul_f32 v[84:85], v[128:129], v[2:3]
	v_pk_mul_f32 v[116:117], v[124:125], v[2:3]
	s_waitcnt lgkmcnt(1)
	s_add_u32 s98, s98, 0x2000
	s_addc_u32 s99, s99, 0
	global_load_dword v237, v151, s[98:99]
	v_mul_f32_e32 v2, 0x3fb8aa3b, v68
	v_mul_f32_e32 v108, 0x3fb8aa3b, v70
	v_mul_f32_e32 v3, 0x3fb8aa3b, v69
	v_exp_f32_e32 v112, v108
	v_mul_f32_e32 v108, 0x3fb8aa3b, v71
	v_exp_f32_e32 v2, v2
	v_exp_f32_e32 v3, v3
	v_exp_f32_e32 v113, v108
	v_pk_mul_f32 v[108:109], v[104:105], v[2:3]
	v_pk_mul_f32 v[110:111], v[106:107], v[112:113]
	s_add_u32 s98, s98, 0x2000
	s_addc_u32 s99, s99, 0
	global_load_dword v236, v151, s[98:99]
	v_pk_mul_f32 v[114:115], v[134:135], v[112:113]
	v_pk_mul_f32 v[112:113], v[132:133], v[2:3]
	s_waitcnt lgkmcnt(0)
	v_mul_f32_e32 v2, 0x3fb8aa3b, v72
	v_mul_f32_e32 v3, 0x3fb8aa3b, v73
	v_mul_f32_e32 v104, 0x3fb8aa3b, v74
	v_mul_f32_e32 v105, 0x3fb8aa3b, v75
	v_exp_f32_e32 v2, v2
	v_exp_f32_e32 v3, v3
	v_exp_f32_e32 v104, v104
	v_exp_f32_e32 v105, v105
	v_pk_mul_f32 v[100:101], v[100:101], v[2:3]
	v_pk_mul_f32 v[102:103], v[102:103], v[104:105]
	v_pk_mul_f32 v[106:107], v[98:99], v[104:105]
	v_pk_mul_f32 v[104:105], v[96:97], v[2:3]
	ds_read_b128 v[96:99], v120 offset:192
	s_waitcnt lgkmcnt(0)
	s_barrier
	v_mul_f32_e32 v2, 0x3fb8aa3b, v96
	v_mul_f32_e32 v3, 0x3fb8aa3b, v97
	v_mul_f32_e32 v96, 0x3fb8aa3b, v98
	v_mul_f32_e32 v97, 0x3fb8aa3b, v99
	v_exp_f32_e32 v2, v2
	v_exp_f32_e32 v3, v3
	v_exp_f32_e32 v96, v96
	v_exp_f32_e32 v97, v97
	v_pk_mul_f32 v[88:89], v[88:89], v[2:3]
	v_pk_mul_f32 v[90:91], v[90:91], v[96:97]
	v_pk_mul_f32 v[98:99], v[94:95], v[96:97]
	v_pk_mul_f32 v[96:97], v[92:93], v[2:3]
	v_mov_b32_e32 v2, s33
	ds_read_b32 v253, v2 offset:252
	ds_read_b128 v[148:151], v209
	ds_read_b128 v[140:143], v209 offset:16
	ds_read_b128 v[144:147], v201
	ds_read_b128 v[124:127], v201 offset:16
	ds_read_b128 v[120:123], v192 offset:53248
	s_waitcnt lgkmcnt(5)
	v_mul_f32_e32 v2, 0x3fb8aa3b, v253
	v_exp_f32_e32 v2, v2
	s_nop 0
	v_pk_mul_f32 v[6:7], v[6:7], v[2:3] op_sel_hi:[1,0]
	v_pk_mul_f32 v[4:5], v[4:5], v[2:3] op_sel_hi:[1,0]
	v_pk_mul_f32 v[74:75], v[10:11], v[2:3] op_sel_hi:[1,0]
	v_pk_mul_f32 v[72:73], v[8:9], v[2:3] op_sel_hi:[1,0]
	v_pk_mul_f32 v[10:11], v[14:15], v[2:3] op_sel_hi:[1,0]
	v_pk_mul_f32 v[8:9], v[12:13], v[2:3] op_sel_hi:[1,0]
	v_pk_mul_f32 v[18:19], v[18:19], v[2:3] op_sel_hi:[1,0]
	v_pk_mul_f32 v[16:17], v[16:17], v[2:3] op_sel_hi:[1,0]
	v_pk_mul_f32 v[14:15], v[22:23], v[2:3] op_sel_hi:[1,0]
	v_pk_mul_f32 v[12:13], v[20:21], v[2:3] op_sel_hi:[1,0]
	v_pk_mul_f32 v[26:27], v[26:27], v[2:3] op_sel_hi:[1,0]
	v_pk_mul_f32 v[24:25], v[24:25], v[2:3] op_sel_hi:[1,0]
	v_pk_mul_f32 v[22:23], v[30:31], v[2:3] op_sel_hi:[1,0]
	v_pk_mul_f32 v[20:21], v[28:29], v[2:3] op_sel_hi:[1,0]
	v_pk_mul_f32 v[34:35], v[34:35], v[2:3] op_sel_hi:[1,0]
	v_pk_mul_f32 v[32:33], v[32:33], v[2:3] op_sel_hi:[1,0]
	v_pk_mul_f32 v[30:31], v[38:39], v[2:3] op_sel_hi:[1,0]
	v_pk_mul_f32 v[28:29], v[36:37], v[2:3] op_sel_hi:[1,0]
	v_pk_mul_f32 v[42:43], v[42:43], v[2:3] op_sel_hi:[1,0]
	v_pk_mul_f32 v[40:41], v[40:41], v[2:3] op_sel_hi:[1,0]
	v_pk_mul_f32 v[38:39], v[46:47], v[2:3] op_sel_hi:[1,0]
	v_pk_mul_f32 v[36:37], v[44:45], v[2:3] op_sel_hi:[1,0]
	v_pk_mul_f32 v[50:51], v[50:51], v[2:3] op_sel_hi:[1,0]
	v_pk_mul_f32 v[48:49], v[48:49], v[2:3] op_sel_hi:[1,0]
	v_pk_mul_f32 v[46:47], v[54:55], v[2:3] op_sel_hi:[1,0]
	v_pk_mul_f32 v[44:45], v[52:53], v[2:3] op_sel_hi:[1,0]
	v_pk_mul_f32 v[58:59], v[58:59], v[2:3] op_sel_hi:[1,0]
	v_pk_mul_f32 v[56:57], v[56:57], v[2:3] op_sel_hi:[1,0]
	v_pk_mul_f32 v[54:55], v[62:63], v[2:3] op_sel_hi:[1,0]
	v_pk_mul_f32 v[52:53], v[60:61], v[2:3] op_sel_hi:[1,0]
	v_pk_mul_f32 v[62:63], v[66:67], v[2:3] op_sel_hi:[1,0]
	v_pk_mul_f32 v[60:61], v[64:65], v[2:3] op_sel_hi:[1,0]
	ds_read_b128 v[64:67], v192 offset:55552
	ds_read_b32 v2, v229
	ds_read_b128 v[68:71], v232
	ds_read_b128 v[76:79], v232 offset:16
	s_waitcnt lgkmcnt(2)
	v_sub_f32_e32 v3, v2, v148
	v_mul_f32_e32 v3, 0x3fb8aa3b, v3
	v_exp_f32_e32 v3, v3
	s_waitcnt lgkmcnt(1)
	v_mul_f32_e32 v3, v68, v3
	v_sub_f32_e32 v68, v2, v149
	v_mul_f32_e32 v68, 0x3fb8aa3b, v68
	v_exp_f32_e32 v68, v68
	v_mul_f32_e32 v3, v144, v3
	v_cndmask_b32_e64 v3, v3, 0, s[24:25]
	v_mul_f32_e32 v68, v69, v68
	v_sub_f32_e32 v69, v2, v150
	v_mul_f32_e32 v69, 0x3fb8aa3b, v69
	v_exp_f32_e32 v69, v69
	v_mul_f32_e32 v68, v145, v68
	v_cndmask_b32_e64 v68, 0, v68, s[26:27]
	ds_read_b32 v80, v229 offset:64
	ds_read_b128 v[128:131], v232 offset:4352
	ds_read_b128 v[132:135], v232 offset:4368
	v_cvt_pk_bf16_f32 v68, v3, v68
	v_mul_f32_e32 v69, v70, v69
	v_sub_f32_e32 v70, v2, v151
	v_mul_f32_e32 v70, 0x3fb8aa3b, v70
	v_exp_f32_e32 v70, v70
	v_mul_f32_e32 v69, v146, v69
	v_cndmask_b32_e64 v69, v69, 0, s[28:29]
	v_mul_f32_e32 v70, v71, v70
	v_sub_f32_e32 v71, v2, v140
	v_mul_f32_e32 v71, 0x3fb8aa3b, v71
	v_exp_f32_e32 v71, v71
	v_mul_f32_e32 v70, v147, v70
	v_cndmask_b32_e64 v70, v70, 0, s[30:31]
	v_cvt_pk_bf16_f32 v69, v69, v70
	s_waitcnt lgkmcnt(3)
	v_mul_f32_e32 v71, v76, v71
	v_sub_f32_e32 v76, v2, v141
	v_mul_f32_e32 v76, 0x3fb8aa3b, v76
	v_exp_f32_e32 v76, v76
	v_mul_f32_e32 v71, v124, v71
	v_cndmask_b32_e64 v71, v71, 0, s[34:35]
	v_mul_f32_e32 v76, v77, v76
	v_sub_f32_e32 v77, v2, v142
	v_sub_f32_e32 v2, v2, v143
	v_mul_f32_e32 v77, 0x3fb8aa3b, v77
	v_mul_f32_e32 v2, 0x3fb8aa3b, v2
	v_exp_f32_e32 v77, v77
	v_exp_f32_e32 v2, v2
	v_mul_f32_e32 v76, v125, v76
	v_cndmask_b32_e64 v76, v76, 0, s[36:37]
	v_mul_f32_e32 v77, v78, v77
	v_mul_f32_e32 v2, v79, v2
	v_mul_f32_e32 v77, v126, v77
	v_mul_f32_e32 v2, v127, v2
	v_cndmask_b32_e64 v77, v77, 0, s[38:39]
	v_cndmask_b32_e64 v2, v2, 0, s[40:41]
	v_cvt_pk_bf16_f32 v70, v71, v76
	v_cvt_pk_bf16_f32 v71, v77, v2
	s_nop 0
	s_nop 0
	v_mfma_f32_16x16x32_bf16 v[92:95], v[68:71], v[120:123], v[84:87]
	v_mfma_f32_16x16x32_bf16 v[84:87], v[68:71], v[64:67], v[116:119]
	s_waitcnt lgkmcnt(2)
	v_sub_f32_e32 v3, v80, v148
	v_mul_f32_e32 v3, 0x3fb8aa3b, v3
	v_exp_f32_e32 v3, v3
	s_waitcnt lgkmcnt(1)
	v_mul_f32_e32 v3, v128, v3
	v_sub_f32_e32 v68, v80, v149
	v_mul_f32_e32 v68, 0x3fb8aa3b, v68
	v_exp_f32_e32 v68, v68
	v_mul_f32_e32 v3, v144, v3
	v_cndmask_b32_e64 v3, v3, 0, s[42:43]
	v_mul_f32_e32 v68, v129, v68
	v_sub_f32_e32 v69, v80, v150
	v_mul_f32_e32 v69, 0x3fb8aa3b, v69
	v_exp_f32_e32 v69, v69
	v_mul_f32_e32 v68, v145, v68
	ds_read_b32 v116, v229 offset:128
	ds_read_b128 v[136:139], v232 offset:8704
	v_cndmask_b32_e64 v68, 0, v68, s[44:45]
	v_cvt_pk_bf16_f32 v68, v3, v68
	v_mul_f32_e32 v69, v130, v69
	v_sub_f32_e32 v70, v80, v151
	v_mul_f32_e32 v70, 0x3fb8aa3b, v70
	v_exp_f32_e32 v70, v70
	v_mul_f32_e32 v69, v146, v69
	v_cndmask_b32_e64 v69, v69, 0, s[46:47]
	v_mul_f32_e32 v70, v131, v70
	v_sub_f32_e32 v71, v80, v140
	v_mul_f32_e32 v71, 0x3fb8aa3b, v71
	v_exp_f32_e32 v71, v71
	v_mul_f32_e32 v70, v147, v70
	v_cndmask_b32_e64 v70, v70, 0, s[48:49]
	v_cvt_pk_bf16_f32 v69, v69, v70
	s_waitcnt lgkmcnt(2)
	v_mul_f32_e32 v71, v132, v71
	v_sub_f32_e32 v76, v80, v141
	v_mul_f32_e32 v76, 0x3fb8aa3b, v76
	v_exp_f32_e32 v76, v76
	v_mul_f32_e32 v71, v124, v71
	v_cndmask_b32_e64 v71, v71, 0, s[50:51]
	v_mul_f32_e32 v76, v133, v76
	v_sub_f32_e32 v77, v80, v142
	v_sub_f32_e32 v2, v80, v143
	v_mul_f32_e32 v77, 0x3fb8aa3b, v77
	v_mul_f32_e32 v2, 0x3fb8aa3b, v2
	v_exp_f32_e32 v77, v77
	v_exp_f32_e32 v2, v2
	v_mul_f32_e32 v76, v125, v76
	v_cndmask_b32_e64 v76, v76, 0, s[52:53]
	v_mul_f32_e32 v77, v134, v77
	v_mul_f32_e32 v2, v135, v2
	v_mul_f32_e32 v77, v126, v77
	v_mul_f32_e32 v2, v127, v2
	v_cndmask_b32_e64 v77, v77, 0, s[54:55]
	v_cndmask_b32_e64 v2, v2, 0, s[56:57]
	v_cvt_pk_bf16_f32 v70, v71, v76
	v_cvt_pk_bf16_f32 v71, v77, v2
	s_nop 0
	s_nop 0
	v_mfma_f32_16x16x32_bf16 v[76:79], v[68:71], v[120:123], v[108:111]
	s_nop 2
	ds_read_b128 v[108:111], v232 offset:8720
	s_nop 0
	s_waitcnt lgkmcnt(2)
	v_sub_f32_e32 v3, v116, v148
	v_mul_f32_e32 v3, 0x3fb8aa3b, v3
	v_exp_f32_e32 v3, v3
	v_mfma_f32_16x16x32_bf16 v[68:71], v[68:71], v[64:67], v[112:115]
	s_waitcnt lgkmcnt(1)
	v_mul_f32_e32 v3, v136, v3
	v_sub_f32_e32 v80, v116, v149
	v_mul_f32_e32 v80, 0x3fb8aa3b, v80
	v_exp_f32_e32 v80, v80
	ds_read_b32 v112, v229 offset:192
	ds_read_b128 v[128:131], v232 offset:13056
	v_mul_f32_e32 v3, v144, v3
	v_mul_f32_e32 v80, v137, v80
	v_sub_f32_e32 v81, v116, v150
	v_mul_f32_e32 v81, 0x3fb8aa3b, v81
	v_exp_f32_e32 v81, v81
	v_mul_f32_e32 v80, v145, v80
	v_cvt_pk_bf16_f32 v80, v3, v80
	v_mul_f32_e32 v81, v138, v81
	v_sub_f32_e32 v82, v116, v151
	v_mul_f32_e32 v82, 0x3fb8aa3b, v82
	v_exp_f32_e32 v82, v82
	v_mul_f32_e32 v81, v146, v81
	v_mul_f32_e32 v82, v139, v82
	v_sub_f32_e32 v83, v116, v140
	v_mul_f32_e32 v83, 0x3fb8aa3b, v83
	v_exp_f32_e32 v83, v83
	v_mul_f32_e32 v82, v147, v82
	v_cvt_pk_bf16_f32 v81, v81, v82
	s_waitcnt lgkmcnt(2)
	v_mul_f32_e32 v83, v108, v83
	v_sub_f32_e32 v108, v116, v141
	v_mul_f32_e32 v108, 0x3fb8aa3b, v108
	v_exp_f32_e32 v108, v108
	v_mul_f32_e32 v83, v124, v83
	v_mul_f32_e32 v108, v109, v108
	v_sub_f32_e32 v109, v116, v142
	v_sub_f32_e32 v2, v116, v143
	v_mul_f32_e32 v109, 0x3fb8aa3b, v109
	v_mul_f32_e32 v2, 0x3fb8aa3b, v2
	v_exp_f32_e32 v109, v109
	v_exp_f32_e32 v2, v2
	v_mul_f32_e32 v108, v125, v108
	v_cvt_pk_bf16_f32 v82, v83, v108
	v_mul_f32_e32 v109, v110, v109
	v_mul_f32_e32 v2, v111, v2
	v_mul_f32_e32 v109, v126, v109
	v_mul_f32_e32 v2, v127, v2
	v_cvt_pk_bf16_f32 v83, v109, v2
	s_nop 0
	s_nop 0
	v_mfma_f32_16x16x32_bf16 v[132:135], v[80:83], v[120:123], v[100:103]
	s_nop 2
	ds_read_b128 v[100:103], v232 offset:13072
	v_mfma_f32_16x16x32_bf16 v[136:139], v[80:83], v[64:67], v[104:107]
	s_waitcnt lgkmcnt(2)
	v_sub_f32_e32 v3, v112, v148
	v_mul_f32_e32 v3, 0x3fb8aa3b, v3
	v_exp_f32_e32 v3, v3
	s_waitcnt lgkmcnt(1)
	v_mul_f32_e32 v3, v128, v3
	v_sub_f32_e32 v80, v112, v149
	v_mul_f32_e32 v80, 0x3fb8aa3b, v80
	v_exp_f32_e32 v80, v80
	v_mul_f32_e32 v3, v144, v3
	v_mul_f32_e32 v80, v129, v80
	v_sub_f32_e32 v81, v112, v150
	v_mul_f32_e32 v81, 0x3fb8aa3b, v81
	v_exp_f32_e32 v81, v81
	v_mul_f32_e32 v80, v145, v80
	v_mul_f32_e32 v81, v130, v81
	v_sub_f32_e32 v82, v112, v151
	v_mul_f32_e32 v82, 0x3fb8aa3b, v82
	v_exp_f32_e32 v82, v82
	v_mul_f32_e32 v81, v146, v81
	v_mul_f32_e32 v82, v131, v82
	v_sub_f32_e32 v83, v112, v140
	v_mul_f32_e32 v83, 0x3fb8aa3b, v83
	v_exp_f32_e32 v83, v83
	v_mul_f32_e32 v82, v147, v82
	s_waitcnt lgkmcnt(0)
	v_mul_f32_e32 v83, v100, v83
	v_sub_f32_e32 v100, v112, v141
	v_mul_f32_e32 v100, 0x3fb8aa3b, v100
	v_exp_f32_e32 v100, v100
	v_mul_f32_e32 v83, v124, v83
	v_mul_f32_e32 v100, v101, v100
	v_mul_f32_e32 v104, v125, v100
	v_sub_f32_e32 v100, v112, v142
	v_sub_f32_e32 v2, v112, v143
	v_mul_f32_e32 v100, 0x3fb8aa3b, v100
	v_mul_f32_e32 v2, 0x3fb8aa3b, v2
	v_exp_f32_e32 v100, v100
	v_exp_f32_e32 v2, v2
	v_mul_f32_e32 v100, v102, v100
	v_mul_f32_e32 v2, v103, v2
	v_mul_f32_e32 v105, v126, v100
	v_mul_f32_e32 v2, v127, v2
	v_cvt_pk_bf16_f32 v100, v3, v80
	v_cvt_pk_bf16_f32 v101, v81, v82
	v_cvt_pk_bf16_f32 v102, v83, v104
	v_cvt_pk_bf16_f32 v103, v105, v2
	v_sub_f32_e32 v2, v253, v148
	s_nop 0
	v_mfma_f32_16x16x32_bf16 v[80:83], v[100:103], v[120:123], v[88:91]
	v_sub_f32_e32 v3, v253, v149
	v_mul_f32_e32 v2, 0x3fb8aa3b, v2
	v_mul_f32_e32 v3, 0x3fb8aa3b, v3
	v_sub_f32_e32 v88, v253, v150
	v_mul_f32_e32 v88, 0x3fb8aa3b, v88
	v_exp_f32_e32 v88, v88
	v_mfma_f32_16x16x32_bf16 v[128:131], v[100:103], v[64:67], v[96:99]
	v_exp_f32_e32 v2, v2
	v_exp_f32_e32 v3, v3
	v_and_b32_e32 v89, 0xffff0000, v120
	v_mul_f32_e32 v96, v146, v88
	v_sub_f32_e32 v88, v253, v151
	v_mul_f32_e32 v88, 0x3fb8aa3b, v88
	v_exp_f32_e32 v88, v88
	v_mul_f32_e32 v2, v144, v2
	v_mul_f32_e32 v3, v145, v3
	v_lshlrev_b32_e32 v90, 16, v121
	v_mul_f32_e32 v97, v147, v88
	v_sub_f32_e32 v88, v253, v140
	v_mul_f32_e32 v88, 0x3fb8aa3b, v88
	v_exp_f32_e32 v88, v88
	v_lshlrev_b32_e32 v102, 16, v122
	v_mul_f32_e32 v89, v3, v89
	v_mul_f32_e32 v90, v96, v90
	v_mul_f32_e32 v98, v124, v88
	v_sub_f32_e32 v88, v253, v141
	v_mul_f32_e32 v88, 0x3fb8aa3b, v88
	v_exp_f32_e32 v88, v88
	v_and_b32_e32 v91, 0xffff0000, v121
	v_mul_f32_e32 v102, v98, v102
	v_and_b32_e32 v103, 0xffff0000, v122
	v_mul_f32_e32 v99, v125, v88
	ds_read_b128 v[106:109], v233 offset:34816
	v_sub_f32_e32 v88, v253, v142
	v_mul_f32_e32 v88, 0x3fb8aa3b, v88
	ds_read_b128 v[110:113], v233 offset:37120
	v_exp_f32_e32 v88, v88
	v_mul_f32_e32 v91, v97, v91
	ds_read_b128 v[114:117], v233 offset:39424
	v_mul_f32_e32 v103, v99, v103
	v_lshlrev_b32_e32 v104, 16, v123
	ds_read_b128 v[144:147], v233 offset:41728
	v_mul_f32_e32 v100, v126, v88
	v_sub_f32_e32 v88, v253, v143
	ds_read_b128 v[148:151], v233 offset:44032
	v_mul_f32_e32 v88, 0x3fb8aa3b, v88
	v_exp_f32_e32 v88, v88
	v_and_b32_e32 v105, 0xffff0000, v123
	v_mul_f32_e32 v104, v100, v104
	v_mul_f32_e32 v101, v127, v88
	v_lshlrev_b32_e32 v88, 16, v120
	v_mul_f32_e32 v88, v2, v88
	v_cvt_pk_bf16_f32 v88, v88, v89
	v_cvt_pk_bf16_f32 v89, v90, v91
	v_cvt_pk_bf16_f32 v90, v102, v103
	v_lshlrev_b32_e32 v102, 16, v64
	v_and_b32_e32 v64, 0xffff0000, v64
	v_mul_f32_e32 v3, v3, v64
	v_lshlrev_b32_e32 v64, 16, v65
	v_mul_f32_e32 v64, v96, v64
	v_lshlrev_b32_e32 v96, 16, v66
	v_and_b32_e32 v65, 0xffff0000, v65
	v_mul_f32_e32 v98, v98, v96
	v_and_b32_e32 v66, 0xffff0000, v66
	v_lshlrev_b32_e32 v96, 16, v67
	v_and_b32_e32 v67, 0xffff0000, v67
	v_mul_f32_e32 v65, v97, v65
	v_mul_f32_e32 v66, v99, v66
	v_mul_f32_e32 v99, v100, v96
	v_mul_f32_e32 v67, v101, v67
	v_mul_f32_e32 v105, v101, v105
	v_cvt_pk_bf16_f32 v91, v104, v105
	v_mul_f32_e32 v2, v2, v102
	v_cvt_pk_bf16_f32 v96, v2, v3
	v_cvt_pk_bf16_f32 v97, v64, v65
	v_cvt_pk_bf16_f32 v98, v98, v66
	v_cvt_pk_bf16_f32 v99, v99, v67
	s_waitcnt lgkmcnt(4)
	v_mfma_f32_16x16x32_bf16 v[2:5], v[106:109], v[88:91], v[4:7]
	v_mfma_f32_16x16x32_bf16 v[140:143], v[106:109], v[96:99], v[72:75]
	s_waitcnt lgkmcnt(3)
	v_mfma_f32_16x16x32_bf16 v[120:123], v[110:113], v[88:91], v[8:11]
	s_nop 2
	ds_read_b128 v[6:9], v233 offset:46336
	s_nop 2
	s_waitcnt lgkmcnt(3)
	v_mfma_f32_16x16x32_bf16 v[124:127], v[114:117], v[88:91], v[12:15]
	v_mfma_f32_16x16x32_bf16 v[24:27], v[114:117], v[96:99], v[24:27]
	s_waitcnt lgkmcnt(2)
	v_mfma_f32_16x16x32_bf16 v[116:119], v[144:147], v[88:91], v[20:23]
	v_mfma_f32_16x16x32_bf16 v[32:35], v[144:147], v[96:99], v[32:35]
	v_mfma_f32_16x16x32_bf16 v[16:19], v[110:113], v[96:99], v[16:19]
	s_waitcnt lgkmcnt(1)
	v_mfma_f32_16x16x32_bf16 v[64:67], v[148:151], v[88:91], v[28:31]
	v_mfma_f32_16x16x32_bf16 v[40:43], v[148:151], v[96:99], v[40:43]
	s_waitcnt lgkmcnt(0)
	v_mfma_f32_16x16x32_bf16 v[100:103], v[6:9], v[88:91], v[36:39]
	v_mfma_f32_16x16x32_bf16 v[48:51], v[6:9], v[96:99], v[48:51]
	ds_read_b128 v[6:9], v233 offset:48640
	s_waitcnt lgkmcnt(0)
	v_mfma_f32_16x16x32_bf16 v[104:107], v[6:9], v[88:91], v[44:47]
	v_mfma_f32_16x16x32_bf16 v[56:59], v[6:9], v[96:99], v[56:59]
	ds_read_b128 v[6:9], v233 offset:50944
	s_nop 0
	ds_read_b128 v[44:47], v209 offset:128
	ds_read_b128 v[28:31], v209 offset:144
	ds_read_b128 v[36:39], v201 offset:128
	ds_read_b128 v[20:23], v201 offset:144
	ds_read_b128 v[10:13], v192 offset:53312
	s_waitcnt lgkmcnt(5)
	v_mfma_f32_16x16x32_bf16 v[108:111], v[6:9], v[88:91], v[52:55]
	v_mfma_f32_16x16x32_bf16 v[112:115], v[6:9], v[96:99], v[60:63]
	ds_read_b128 v[6:9], v192 offset:55616
	ds_read_b32 v14, v229 offset:128
	ds_read_b128 v[52:55], v232 offset:8832
	ds_read_b128 v[60:63], v232 offset:8848
	s_waitcnt lgkmcnt(2)
	v_sub_f32_e32 v15, v14, v44
	v_mul_f32_e32 v15, 0x3fb8aa3b, v15
	v_exp_f32_e32 v15, v15
	s_waitcnt lgkmcnt(1)
	v_mul_f32_e32 v15, v52, v15
	v_sub_f32_e32 v52, v14, v45
	v_mul_f32_e32 v52, 0x3fb8aa3b, v52
	v_exp_f32_e32 v52, v52
	v_mul_f32_e32 v15, v36, v15
	v_cndmask_b32_e64 v15, v15, 0, s[24:25]
	v_mul_f32_e32 v52, v53, v52
	v_sub_f32_e32 v53, v14, v46
	v_mul_f32_e32 v53, 0x3fb8aa3b, v53
	v_exp_f32_e32 v53, v53
	v_mul_f32_e32 v52, v37, v52
	v_cndmask_b32_e64 v52, v52, 0, s[58:59]
	ds_read_b32 v72, v229 offset:192
	ds_read_b128 v[144:147], v232 offset:13184
	ds_read_b128 v[148:151], v232 offset:13200
	v_cvt_pk_bf16_f32 v52, v15, v52
	v_mul_f32_e32 v53, v54, v53
	v_sub_f32_e32 v54, v14, v47
	v_mul_f32_e32 v54, 0x3fb8aa3b, v54
	v_exp_f32_e32 v54, v54
	v_mul_f32_e32 v53, v38, v53
	v_cndmask_b32_e64 v53, v53, 0, s[60:61]
	v_mul_f32_e32 v54, v55, v54
	v_sub_f32_e32 v55, v14, v28
	v_mul_f32_e32 v55, 0x3fb8aa3b, v55
	v_exp_f32_e32 v55, v55
	v_mul_f32_e32 v54, v39, v54
	v_cndmask_b32_e64 v54, v54, 0, s[62:63]
	v_cvt_pk_bf16_f32 v53, v53, v54
	s_waitcnt lgkmcnt(3)
	v_mul_f32_e32 v55, v60, v55
	v_sub_f32_e32 v60, v14, v29
	v_mul_f32_e32 v60, 0x3fb8aa3b, v60
	v_exp_f32_e32 v60, v60
	v_mul_f32_e32 v55, v20, v55
	v_cndmask_b32_e64 v55, v55, 0, s[64:65]
	v_mul_f32_e32 v60, v61, v60
	v_sub_f32_e32 v61, v14, v30
	v_sub_f32_e32 v14, v14, v31
	v_mul_f32_e32 v61, 0x3fb8aa3b, v61
	v_mul_f32_e32 v14, 0x3fb8aa3b, v14
	v_exp_f32_e32 v61, v61
	v_exp_f32_e32 v14, v14
	v_mul_f32_e32 v60, v21, v60
	v_cndmask_b32_e64 v60, v60, 0, s[66:67]
	v_mul_f32_e32 v61, v62, v61
	v_mul_f32_e32 v14, v63, v14
	v_mul_f32_e32 v61, v22, v61
	v_mul_f32_e32 v14, v23, v14
	v_cndmask_b32_e64 v61, v61, 0, s[68:69]
	v_cndmask_b32_e64 v14, v14, 0, s[70:71]
	v_cvt_pk_bf16_f32 v54, v55, v60
	v_cvt_pk_bf16_f32 v55, v61, v14
	s_nop 0
	s_nop 0
	v_mfma_f32_16x16x32_bf16 v[96:99], v[52:55], v[10:13], v[132:135]
	v_mfma_f32_16x16x32_bf16 v[88:91], v[52:55], v[6:9], v[136:139]
	s_waitcnt lgkmcnt(2)
	v_sub_f32_e32 v15, v72, v44
	v_mul_f32_e32 v15, 0x3fb8aa3b, v15
	v_exp_f32_e32 v15, v15
	s_waitcnt lgkmcnt(1)
	v_mul_f32_e32 v15, v144, v15
	v_sub_f32_e32 v52, v72, v45
	v_mul_f32_e32 v52, 0x3fb8aa3b, v52
	v_exp_f32_e32 v52, v52
	v_mul_f32_e32 v15, v36, v15
	v_cndmask_b32_e64 v15, v15, 0, s[72:73]
	v_mul_f32_e32 v52, v145, v52
	v_sub_f32_e32 v53, v72, v46
	v_mul_f32_e32 v53, 0x3fb8aa3b, v53
	v_exp_f32_e32 v53, v53
	v_mul_f32_e32 v52, v37, v52
	v_cndmask_b32_e64 v52, v52, 0, s[74:75]
	v_cvt_pk_bf16_f32 v52, v15, v52
	v_mul_f32_e32 v53, v146, v53
	v_sub_f32_e32 v54, v72, v47
	v_mul_f32_e32 v54, 0x3fb8aa3b, v54
	v_exp_f32_e32 v54, v54
	v_mul_f32_e32 v53, v38, v53
	v_cndmask_b32_e64 v53, v53, 0, s[76:77]
	v_sub_f32_e32 v15, v253, v45
	v_mul_f32_e32 v54, v147, v54
	v_sub_f32_e32 v55, v72, v28
	v_mul_f32_e32 v55, 0x3fb8aa3b, v55
	v_exp_f32_e32 v55, v55
	v_sub_f32_e32 v28, v253, v28
	v_mul_f32_e32 v28, 0x3fb8aa3b, v28
	v_exp_f32_e32 v28, v28
	s_waitcnt lgkmcnt(0)
	v_mul_f32_e32 v55, v148, v55
	v_sub_f32_e32 v60, v72, v29
	v_mul_f32_e32 v60, 0x3fb8aa3b, v60
	v_exp_f32_e32 v60, v60
	v_mul_f32_e32 v55, v20, v55
	v_mul_f32_e32 v20, v20, v28
	v_sub_f32_e32 v28, v253, v29
	v_mul_f32_e32 v60, v149, v60
	v_sub_f32_e32 v61, v72, v30
	v_sub_f32_e32 v14, v72, v31
	v_mul_f32_e32 v14, 0x3fb8aa3b, v14
	v_mul_f32_e32 v61, 0x3fb8aa3b, v61
	v_exp_f32_e32 v14, v14
	v_exp_f32_e32 v61, v61
	v_mul_f32_e32 v28, 0x3fb8aa3b, v28
	v_exp_f32_e32 v28, v28
	v_mul_f32_e32 v14, v151, v14
	v_mul_f32_e32 v54, v39, v54
	v_mul_f32_e32 v61, v150, v61
	v_mul_f32_e32 v14, v23, v14
	v_cndmask_b32_e64 v54, v54, 0, s[78:79]
	v_cndmask_b32_e64 v55, v55, 0, s[80:81]
	v_mul_f32_e32 v60, v21, v60
	v_mul_f32_e32 v61, v22, v61
	v_cndmask_b32_e64 v14, v14, 0, s[86:87]
	v_mul_f32_e32 v21, v21, v28
	v_sub_f32_e32 v28, v253, v30
	v_cndmask_b32_e64 v60, v60, 0, s[82:83]
	v_cndmask_b32_e64 v61, v61, 0, s[84:85]
	v_cvt_pk_bf16_f32 v53, v53, v54
	v_cvt_pk_bf16_f32 v54, v55, v60
	v_cvt_pk_bf16_f32 v55, v61, v14
	v_sub_f32_e32 v14, v253, v44
	v_mul_f32_e32 v15, 0x3fb8aa3b, v15
	v_mul_f32_e32 v28, 0x3fb8aa3b, v28
	v_mul_f32_e32 v14, 0x3fb8aa3b, v14
	v_exp_f32_e32 v15, v15
	v_exp_f32_e32 v28, v28
	v_exp_f32_e32 v14, v14
	v_mfma_f32_16x16x32_bf16 v[80:83], v[52:55], v[10:13], v[80:83]
	v_mul_f32_e32 v15, v37, v15
	v_sub_f32_e32 v37, v253, v47
	v_mul_f32_e32 v22, v22, v28
	v_sub_f32_e32 v28, v253, v31
	v_mul_f32_e32 v14, v36, v14
	v_sub_f32_e32 v36, v253, v46
	v_mul_f32_e32 v37, 0x3fb8aa3b, v37
	v_mul_f32_e32 v28, 0x3fb8aa3b, v28
	v_mul_f32_e32 v36, 0x3fb8aa3b, v36
	v_exp_f32_e32 v37, v37
	v_exp_f32_e32 v28, v28
	v_exp_f32_e32 v36, v36
	v_lshlrev_b32_e32 v29, 16, v11
	v_mul_f32_e32 v37, v39, v37
	v_mul_f32_e32 v23, v23, v28
	v_lshlrev_b32_e32 v28, 16, v10
	ds_read_b128 v[132:135], v233 offset:34880
	ds_read_b128 v[136:139], v233 offset:37184
	ds_read_b128 v[144:147], v233 offset:39488
	ds_read_b128 v[148:151], v233 offset:41792
	ds_read_b128 v[44:47], v233 offset:44096
	v_and_b32_e32 v10, 0xffff0000, v10
	v_and_b32_e32 v11, 0xffff0000, v11
	v_lshlrev_b32_e32 v30, 16, v12
	v_and_b32_e32 v12, 0xffff0000, v12
	v_lshlrev_b32_e32 v31, 16, v13
	v_and_b32_e32 v13, 0xffff0000, v13
	v_mul_f32_e32 v36, v38, v36
	v_mul_f32_e32 v10, v15, v10
	v_mul_f32_e32 v11, v37, v11
	v_mul_f32_e32 v12, v21, v12
	v_mul_f32_e32 v13, v23, v13
	v_mfma_f32_16x16x32_bf16 v[72:75], v[52:55], v[6:9], v[128:131]
	ds_read_b128 v[52:55], v233 offset:46400
	v_mul_f32_e32 v28, v14, v28
	v_mul_f32_e32 v29, v36, v29
	v_mul_f32_e32 v30, v20, v30
	v_mul_f32_e32 v31, v22, v31
	v_cvt_pk_bf16_f32 v60, v28, v10
	v_cvt_pk_bf16_f32 v61, v29, v11
	v_cvt_pk_bf16_f32 v62, v30, v12
	v_cvt_pk_bf16_f32 v63, v31, v13
	v_lshlrev_b32_e32 v10, 16, v6
	v_lshlrev_b32_e32 v11, 16, v7
	v_lshlrev_b32_e32 v12, 16, v8
	v_and_b32_e32 v8, 0xffff0000, v8
	v_lshlrev_b32_e32 v13, 16, v9
	v_and_b32_e32 v9, 0xffff0000, v9
	v_mul_f32_e32 v10, v14, v10
	v_and_b32_e32 v6, 0xffff0000, v6
	v_mul_f32_e32 v11, v36, v11
	v_and_b32_e32 v7, 0xffff0000, v7
	v_mul_f32_e32 v8, v21, v8
	v_mul_f32_e32 v9, v23, v9
	v_mul_f32_e32 v6, v15, v6
	v_mul_f32_e32 v7, v37, v7
	v_mul_f32_e32 v12, v20, v12
	v_mul_f32_e32 v13, v22, v13
	v_cvt_pk_bf16_f32 v128, v10, v6
	v_cvt_pk_bf16_f32 v129, v11, v7
	v_cvt_pk_bf16_f32 v130, v12, v8
	v_cvt_pk_bf16_f32 v131, v13, v9
	s_waitcnt lgkmcnt(4)
	v_mfma_f32_16x16x32_bf16 v[12:15], v[136:139], v[60:63], v[120:123]
	v_mfma_f32_16x16x32_bf16 v[16:19], v[136:139], v[128:131], v[16:19]
	s_waitcnt lgkmcnt(3)
	v_mfma_f32_16x16x32_bf16 v[20:23], v[144:147], v[60:63], v[124:127]
	v_mfma_f32_16x16x32_bf16 v[24:27], v[144:147], v[128:131], v[24:27]
	s_waitcnt lgkmcnt(2)
	v_mfma_f32_16x16x32_bf16 v[28:31], v[148:151], v[60:63], v[116:119]
	v_mfma_f32_16x16x32_bf16 v[32:35], v[148:151], v[128:131], v[32:35]
	s_waitcnt lgkmcnt(1)
	v_mfma_f32_16x16x32_bf16 v[36:39], v[44:47], v[60:63], v[64:67]
	s_nop 2
	ds_read_b128 v[64:67], v233 offset:48704
	s_nop 2
	v_mfma_f32_16x16x32_bf16 v[4:7], v[132:135], v[60:63], v[2:5]
	s_nop 2
	ds_read_b64 v[2:3], v234 offset:53248
	ds_read_u16 v192, v235
	v_mfma_f32_16x16x32_bf16 v[40:43], v[44:47], v[128:131], v[40:43]
	s_nop 1
	s_waitcnt lgkmcnt(3)
	v_mfma_f32_16x16x32_bf16 v[44:47], v[52:55], v[60:63], v[100:103]
	s_nop 2
	ds_read_u16 v103, v235 offset:528
	v_mfma_f32_16x16x32_bf16 v[48:51], v[52:55], v[128:131], v[48:51]
	s_nop 1
	s_waitcnt lgkmcnt(2)
	v_lshlrev_b32_e32 v100, 16, v2
	v_mfma_f32_16x16x32_bf16 v[52:55], v[64:67], v[60:63], v[104:107]
	v_and_b32_e32 v101, 0xffff0000, v2
	s_waitcnt lgkmcnt(1)
	v_lshlrev_b32_e32 v102, 16, v192
	s_waitcnt lgkmcnt(0)
	v_lshlrev_b32_e32 v103, 16, v103
	v_mfma_f32_16x16x32_bf16 v[56:59], v[64:67], v[128:131], v[56:59]
	ds_read_b128 v[64:67], v233 offset:51008
	ds_read_u16 v116, v235 offset:1056
	ds_read_u16 v117, v235 offset:1584
	ds_read_b64 v[104:105], v234 offset:55552
	ds_read_u16 v106, v235 offset:32
	ds_read_u16 v107, v235 offset:560
	v_pk_fma_f32 v[92:93], v[154:155], v[100:101], v[92:93]
	v_pk_mul_f32 v[100:101], v[102:103], s[96:97] op_sel_hi:[1,0]
	v_lshlrev_b32_e32 v2, 16, v3
	v_exp_f32_e32 v100, v100
	v_exp_f32_e32 v101, v101
	v_and_b32_e32 v3, 0xffff0000, v3
	v_pk_fma_f32 v[2:3], v[154:155], v[2:3], v[94:95]
	v_mfma_f32_16x16x32_bf16 v[8:11], v[132:135], v[128:131], v[140:143]
	v_add_f32_e64 v100, v100, 1.0
	v_add_f32_e64 v101, v101, 1.0
	v_rcp_f32_e32 v100, v100
	v_rcp_f32_e32 v101, v101
	s_waitcnt lgkmcnt(5)
	v_mfma_f32_16x16x32_bf16 v[60:63], v[64:67], v[60:63], v[108:111]
	v_mul_f32_e64 v100, v100, v102
	v_mul_f32_e64 v101, v101, v103
	v_pk_mul_f32 v[92:93], v[92:93], v[100:101]
	v_mfma_f32_16x16x32_bf16 v[64:67], v[64:67], v[128:131], v[112:115]
	v_cvt_pk_bf16_f32 v102, v92, v93
	ds_write_b16 v235, v102
	ds_write_b16_d16_hi v235, v102 offset:528
	s_waitcnt lgkmcnt(6)
	v_lshlrev_b32_e32 v92, 16, v116
	s_waitcnt lgkmcnt(5)
	v_lshlrev_b32_e32 v93, 16, v117
	ds_read_u16 v108, v235 offset:1088
	ds_read_u16 v109, v235 offset:1616
	v_pk_mul_f32 v[94:95], v[92:93], s[96:97] op_sel_hi:[1,0]
	s_nop 0
	v_exp_f32_e32 v94, v94
	v_exp_f32_e32 v95, v95
	s_nop 0
	v_pk_add_f32 v[94:95], v[94:95], 1.0 op_sel_hi:[1,0]
	s_nop 0
	v_rcp_f32_e32 v94, v94
	v_rcp_f32_e32 v95, v95
	s_nop 0
	v_pk_mul_f32 v[92:93], v[94:95], v[92:93]
	s_nop 0
	v_pk_mul_f32 v[2:3], v[2:3], v[92:93]
	s_nop 0
	v_cvt_pk_bf16_f32 v103, v2, v3
	ds_write_b16 v235, v103 offset:1056
	ds_write_b16_d16_hi v235, v103 offset:1584
	s_waitcnt lgkmcnt(8)
	v_lshlrev_b32_e32 v92, 16, v104
	v_and_b32_e32 v93, 0xffff0000, v104
	s_waitcnt lgkmcnt(7)
	v_lshlrev_b32_e32 v94, 16, v106
	s_waitcnt lgkmcnt(6)
	v_lshlrev_b32_e32 v95, 16, v107
	v_pk_fma_f32 v[84:85], v[154:155], v[92:93], v[84:85]
	v_pk_mul_f32 v[92:93], v[94:95], s[96:97] op_sel_hi:[1,0]
	v_lshlrev_b32_e32 v2, 16, v105
	v_exp_f32_e32 v92, v92
	v_exp_f32_e32 v93, v93
	v_and_b32_e32 v3, 0xffff0000, v105
	v_pk_fma_f32 v[2:3], v[154:155], v[2:3], v[86:87]
	v_pk_add_f32 v[92:93], v[92:93], 1.0 op_sel_hi:[1,0]
	s_nop 0
	v_rcp_f32_e32 v92, v92
	v_rcp_f32_e32 v93, v93
	s_nop 0
	v_pk_mul_f32 v[92:93], v[92:93], v[94:95]
	s_nop 0
	v_pk_mul_f32 v[84:85], v[84:85], v[92:93]
	s_nop 0
	v_cvt_pk_bf16_f32 v92, v84, v85
	ds_write_b16 v235, v92 offset:32
	ds_write_b16_d16_hi v235, v92 offset:560
	s_waitcnt lgkmcnt(5)
	v_lshlrev_b32_e32 v84, 16, v108
	s_waitcnt lgkmcnt(4)
	v_lshlrev_b32_e32 v85, 16, v109
	v_pk_mul_f32 v[86:87], v[84:85], s[96:97] op_sel_hi:[1,0]
	s_nop 0
	v_exp_f32_e32 v86, v86
	v_exp_f32_e32 v87, v87
	s_nop 0
	v_pk_add_f32 v[86:87], v[86:87], 1.0 op_sel_hi:[1,0]
	s_nop 0
	v_rcp_f32_e32 v86, v86
	v_rcp_f32_e32 v87, v87
	s_nop 0
	v_pk_mul_f32 v[84:85], v[86:87], v[84:85]
	s_nop 0
	v_pk_mul_f32 v[2:3], v[2:3], v[84:85]
	v_lshlrev_b32_e32 v84, 16, v92
	v_cvt_pk_bf16_f32 v93, v2, v3
	ds_write_b16 v235, v93 offset:1088
	ds_write_b16_d16_hi v235, v93 offset:1616
	v_and_b32_e32 v85, 0xffff0000, v92
	v_lshlrev_b32_e32 v92, 16, v93
	v_and_b32_e32 v93, 0xffff0000, v93
	v_pk_mul_f32 v[84:85], v[84:85], v[84:85]
	v_and_b32_e32 v3, 0xffff0000, v102
	v_lshlrev_b32_e32 v86, 16, v103
	v_lshlrev_b32_e32 v2, 16, v102
	v_and_b32_e32 v87, 0xffff0000, v103
	v_pk_mul_f32 v[92:93], v[92:93], v[92:93]
	v_pk_fma_f32 v[2:3], v[2:3], v[2:3], v[84:85]
	v_pk_fma_f32 v[86:87], v[86:87], v[86:87], v[92:93]
	s_nop 0
	v_add_u32_e32 v102, s12, v156
	v_add_f32_dpp v2, v2, v2 quad_perm:[1,0,3,2] row_mask:0xf bank_mask:0xf
	v_add_f32_dpp v3, v3, v3 quad_perm:[1,0,3,2] row_mask:0xf bank_mask:0xf
	v_add_f32_dpp v86, v86, v86 quad_perm:[1,0,3,2] row_mask:0xf bank_mask:0xf
	v_add_f32_dpp v87, v87, v87 quad_perm:[1,0,3,2] row_mask:0xf bank_mask:0xf
	v_add_f32_dpp v2, v2, v2 quad_perm:[2,3,0,1] row_mask:0xf bank_mask:0xf
	v_add_f32_dpp v3, v3, v3 quad_perm:[2,3,0,1] row_mask:0xf bank_mask:0xf
	v_add_f32_dpp v86, v86, v86 quad_perm:[2,3,0,1] row_mask:0xf bank_mask:0xf
	v_add_f32_dpp v87, v87, v87 quad_perm:[2,3,0,1] row_mask:0xf bank_mask:0xf
	v_add_f32_dpp v2, v2, v2 row_half_mirror row_mask:0xf bank_mask:0xf
	v_add_f32_dpp v3, v3, v3 row_half_mirror row_mask:0xf bank_mask:0xf
	v_add_f32_dpp v86, v86, v86 row_half_mirror row_mask:0xf bank_mask:0xf
	v_add_f32_dpp v87, v87, v87 row_half_mirror row_mask:0xf bank_mask:0xf
	v_add_f32_dpp v84, v2, v2 row_mirror row_mask:0xf bank_mask:0xf
	v_add_f32_dpp v85, v3, v3 row_mirror row_mask:0xf bank_mask:0xf
	v_add_f32_dpp v86, v86, v86 row_mirror row_mask:0xf bank_mask:0xf
	v_add_f32_dpp v87, v87, v87 row_mirror row_mask:0xf bank_mask:0xf
	s_and_saveexec_b64 s[94:95], s[10:11]
	s_cbranch_execz .LBB0_382
	ds_write_b128 v102, v[84:87]
